# scan loop: three fillers in two of the DPP-chain gaps (B prefetch and free butterfly ops moved up), same instruction count
# baseline (speedup 1.0000x reference)
; __device__ void scan_block(const Params& P, int sb, unsigned char* lds) {
;     ...
;       for (int s = 0; s < SC_CH; ++s) {
;         f32x4 w4n, k4n, b4n, kh4n, r4n; float vn;
;         if (s + 1 < SC_CH) {
;           const float* qn = q + (s + 1) * SC_STEP;
;           w4n = *(const f32x4*)(qn); k4n = *(const f32x4*)(qn + 64); b4n = *(const f32x4*)(qn + 128); kh4n = *(const f32x4*)(qn + 192); r4n = *(const f32x4*)(qn + 256);
;           vn = qv[(s + 1) * SC_STEP];
;         }
;         __builtin_amdgcn_sched_barrier(0);
;         if (s > 0) {
;           const float y = dpp_allreduce16(ypart);
;           yk = (ks == ((s - 1) & 15)) ? y : yk;
;           if (((s - 1) & 15) == 15) yo[(size_t)(s - 16) * 1024] = yk;
;         }
;         const f32x2 pp = (f32x2){S[0], S[1]} * (f32x2){k4[0], k4[1]} + (f32x2){S[2], S[3]} * (f32x2){k4[2], k4[3]};
;         const f32x4 A = S * w4 + v * kh4;
;         const float ar = dpp_allreduce16(pp.x + pp.y);
;         S = A + ar * b4;
;         const f32x2 yy = (f32x2){S[0], S[1]} * (f32x2){r4[0], r4[1]} + (f32x2){S[2], S[3]} * (f32x2){r4[2], r4[3]};
;         ypart = yy.x + yy.y;
;         if (s + 1 < SC_CH) { w4 = w4n; k4 = k4n; b4 = b4n; kh4 = kh4n; r4 = r4n; v = vn; }
;       }
.Lscan_top:
	s_waitcnt lgkmcnt(6)
	v_pk_mul_f32 v[52:53], v[6:7], v[14:15]
	v_pk_mul_f32 v[56:57], v[6:7], v[18:19]
	v_pk_fma_f32 v[52:53], v[4:5], v[12:13], v[52:53]
	v_pk_mul_f32 v[54:55], v[4:5], v[16:17]
	v_add_f32_e32 v52, v52, v53
	ds_read_b128 v[76:79], v9 offset:4288
	ds_read_b128 v[80:83], v9 offset:4032
	v_add_f32_dpp v52, v52, v52 quad_perm:[1,0,3,2] row_mask:0xf bank_mask:0xf bound_ctrl:1
	v_pk_fma_f32 v[56:57], v[22:23], v[24:25], v[56:57] op_sel_hi:[1,0,1]
	v_pk_fma_f32 v[54:55], v[20:21], v[24:25], v[54:55] op_sel_hi:[1,0,1]
	v_add_f32_dpp v52, v52, v52 quad_perm:[2,3,0,1] row_mask:0xf bank_mask:0xf bound_ctrl:1
	ds_read_b128 v[88:91], v9 offset:4800
	ds_read_b32 v94, v10 offset:5312
	v_add_f32_dpp v52, v52, v52 row_half_mirror row_mask:0xf bank_mask:0xf bound_ctrl:1
	s_nop 1
	ds_read_b128 v[108:111], v9 offset:4544
	v_add_f32_dpp v52, v52, v52 row_mirror row_mask:0xf bank_mask:0xf bound_ctrl:1
	v_pk_fma_f32 v[6:7], v[46:47], v[52:53], v[56:57] op_sel_hi:[1,0,1]
	v_pk_fma_f32 v[4:5], v[44:45], v[52:53], v[54:55] op_sel_hi:[1,0,1]
	ds_read_b128 v[96:99], v9 offset:3712
	v_pk_mul_f32 v[52:53], v[6:7], v[62:63]
	v_pk_mul_f32 v[56:57], v[6:7], v[66:67]
	v_pk_fma_f32 v[52:53], v[4:5], v[60:61], v[52:53]
	v_pk_mul_f32 v[54:55], v[4:5], v[64:65]
	v_add_f32_e32 v52, v52, v53
	ds_read_b128 v[12:15], v9 offset:5632
	ds_read_b128 v[16:19], v9 offset:5376
	v_add_f32_dpp v52, v52, v52 quad_perm:[1,0,3,2] row_mask:0xf bank_mask:0xf bound_ctrl:1
	v_pk_fma_f32 v[56:57], v[30:31], v[32:33], v[56:57] op_sel_hi:[1,0,1]
	v_pk_fma_f32 v[54:55], v[28:29], v[32:33], v[54:55] op_sel_hi:[1,0,1]
	v_add_f32_dpp v52, v52, v52 quad_perm:[2,3,0,1] row_mask:0xf bank_mask:0xf bound_ctrl:1
	ds_read_b128 v[20:23], v9 offset:6144
	ds_read_b32 v24, v10 offset:6656
	v_add_f32_dpp v52, v52, v52 row_half_mirror row_mask:0xf bank_mask:0xf bound_ctrl:1
	v_pk_mul_f32 v[26:27], v[6:7], v[38:39]
	s_nop 0
	ds_read_b128 v[44:47], v9 offset:5888
	v_add_f32_dpp v52, v52, v52 row_mirror row_mask:0xf bank_mask:0xf bound_ctrl:1
	v_pk_fma_f32 v[6:7], v[50:51], v[52:53], v[56:57] op_sel_hi:[1,0,1]
	v_pk_fma_f32 v[26:27], v[4:5], v[36:37], v[26:27]
	v_pk_fma_f32 v[4:5], v[48:49], v[52:53], v[54:55] op_sel_hi:[1,0,1]
	ds_read_b128 v[100:103], v9 offset:5056
	v_add_f32_e32 v25, v26, v27
	s_waitcnt lgkmcnt(6)
	v_pk_mul_f32 v[52:53], v[6:7], v[70:71]
	v_pk_mul_f32 v[56:57], v[6:7], v[74:75]
	v_pk_fma_f32 v[52:53], v[4:5], v[68:69], v[52:53]
	v_pk_mul_f32 v[54:55], v[4:5], v[72:73]
	v_add_f32_e32 v52, v52, v53
	ds_read_b128 v[60:63], v9 offset:6976
	ds_read_b128 v[64:67], v9 offset:6720
	v_add_f32_dpp v52, v52, v52 quad_perm:[1,0,3,2] row_mask:0xf bank_mask:0xf bound_ctrl:1
	v_pk_fma_f32 v[56:57], v[86:87], v[92:93], v[56:57] op_sel_hi:[1,0,1]
	v_pk_fma_f32 v[54:55], v[84:85], v[92:93], v[54:55] op_sel_hi:[1,0,1]
	v_add_f32_dpp v52, v52, v52 quad_perm:[2,3,0,1] row_mask:0xf bank_mask:0xf bound_ctrl:1
	ds_read_b128 v[28:31], v9 offset:7488
	ds_read_b32 v32, v10 offset:8000
	v_add_f32_dpp v52, v52, v52 row_half_mirror row_mask:0xf bank_mask:0xf bound_ctrl:1
	v_pk_mul_f32 v[26:27], v[6:7], v[42:43]
	v_add_f32_dpp v34, v25, v25 row_ror:8 row_mask:0xf bank_mask:0x3
	ds_read_b128 v[48:51], v9 offset:7232
	v_add_f32_dpp v52, v52, v52 row_mirror row_mask:0xf bank_mask:0xf bound_ctrl:1
	v_pk_fma_f32 v[6:7], v[106:107], v[52:53], v[56:57] op_sel_hi:[1,0,1]
	v_pk_fma_f32 v[26:27], v[4:5], v[40:41], v[26:27]
	v_pk_fma_f32 v[4:5], v[104:105], v[52:53], v[54:55] op_sel_hi:[1,0,1]
	ds_read_b128 v[36:39], v9 offset:6400
	v_add_f32_e32 v25, v26, v27
	v_pk_mul_f32 v[52:53], v[6:7], v[78:79]
	v_pk_mul_f32 v[56:57], v[6:7], v[82:83]
	v_pk_fma_f32 v[52:53], v[4:5], v[76:77], v[52:53]
	v_pk_mul_f32 v[54:55], v[4:5], v[80:81]
	v_add_f32_e32 v52, v52, v53
	ds_read_b128 v[68:71], v9 offset:8320
	ds_read_b128 v[72:75], v9 offset:8064
	v_add_f32_dpp v52, v52, v52 quad_perm:[1,0,3,2] row_mask:0xf bank_mask:0xf bound_ctrl:1
	v_pk_fma_f32 v[56:57], v[90:91], v[94:95], v[56:57] op_sel_hi:[1,0,1]
	v_pk_fma_f32 v[54:55], v[88:89], v[94:95], v[54:55] op_sel_hi:[1,0,1]
	v_add_f32_dpp v52, v52, v52 quad_perm:[2,3,0,1] row_mask:0xf bank_mask:0xf bound_ctrl:1
	ds_read_b128 v[84:87], v9 offset:8832
	ds_read_b32 v92, v10 offset:9344
	v_add_f32_dpp v52, v52, v52 row_half_mirror row_mask:0xf bank_mask:0xf bound_ctrl:1
	v_pk_mul_f32 v[26:27], v[6:7], v[98:99]
	v_add_f32_dpp v34, v25, v25 row_ror:8 row_mask:0xf bank_mask:0xc
	ds_read_b128 v[104:107], v9 offset:8576
	v_add_f32_dpp v52, v52, v52 row_mirror row_mask:0xf bank_mask:0xf bound_ctrl:1
	v_pk_fma_f32 v[6:7], v[110:111], v[52:53], v[56:57] op_sel_hi:[1,0,1]
	v_pk_fma_f32 v[26:27], v[4:5], v[96:97], v[26:27]
	v_pk_fma_f32 v[4:5], v[108:109], v[52:53], v[54:55] op_sel_hi:[1,0,1]
	ds_read_b128 v[40:43], v9 offset:7744
	v_add_f32_e32 v25, v26, v27
	v_add_f32_dpp v35, v34, v34 row_half_mirror row_mask:0xf bank_mask:0x5
	s_waitcnt lgkmcnt(6)
; __device__ void scan_block(const Params& P, int sb, unsigned char* lds) {
;     ...
;       for (int s = 0; s < SC_CH; ++s) {
;         f32x4 w4n, k4n, b4n, kh4n, r4n; float vn;
;         if (s + 1 < SC_CH) {
;           const float* qn = q + (s + 1) * SC_STEP;
;           w4n = *(const f32x4*)(qn); k4n = *(const f32x4*)(qn + 64); b4n = *(const f32x4*)(qn + 128); kh4n = *(const f32x4*)(qn + 192); r4n = *(const f32x4*)(qn + 256);
;           vn = qv[(s + 1) * SC_STEP];
;         }
;         __builtin_amdgcn_sched_barrier(0);
;         if (s > 0) {
;           const float y = dpp_allreduce16(ypart);
;           yk = (ks == ((s - 1) & 15)) ? y : yk;
;           if (((s - 1) & 15) == 15) yo[(size_t)(s - 16) * 1024] = yk;
;         }
;         const f32x2 pp = (f32x2){S[0], S[1]} * (f32x2){k4[0], k4[1]} + (f32x2){S[2], S[3]} * (f32x2){k4[2], k4[3]};
;         const f32x4 A = S * w4 + v * kh4;
;         const float ar = dpp_allreduce16(pp.x + pp.y);
;         S = A + ar * b4;
;         const f32x2 yy = (f32x2){S[0], S[1]} * (f32x2){r4[0], r4[1]} + (f32x2){S[2], S[3]} * (f32x2){r4[2], r4[3]};
;         ypart = yy.x + yy.y;
;         if (s + 1 < SC_CH) { w4 = w4n; k4 = k4n; b4 = b4n; kh4 = kh4n; r4 = r4n; v = vn; }
;       }
	v_pk_mul_f32 v[52:53], v[6:7], v[14:15]
	v_pk_mul_f32 v[56:57], v[6:7], v[18:19]
	v_pk_fma_f32 v[52:53], v[4:5], v[12:13], v[52:53]
	v_pk_mul_f32 v[54:55], v[4:5], v[16:17]
	v_add_f32_e32 v52, v52, v53
	ds_read_b128 v[76:79], v9 offset:9664
	ds_read_b128 v[80:83], v9 offset:9408
	v_add_f32_dpp v52, v52, v52 quad_perm:[1,0,3,2] row_mask:0xf bank_mask:0xf bound_ctrl:1
	v_pk_fma_f32 v[56:57], v[22:23], v[24:25], v[56:57] op_sel_hi:[1,0,1]
	v_pk_fma_f32 v[54:55], v[20:21], v[24:25], v[54:55] op_sel_hi:[1,0,1]
	v_add_f32_dpp v52, v52, v52 quad_perm:[2,3,0,1] row_mask:0xf bank_mask:0xf bound_ctrl:1
	ds_read_b128 v[88:91], v9 offset:10176
	ds_read_b32 v94, v10 offset:10688
	v_add_f32_dpp v52, v52, v52 row_half_mirror row_mask:0xf bank_mask:0xf bound_ctrl:1
	v_pk_mul_f32 v[26:27], v[6:7], v[102:103]
	v_add_f32_dpp v34, v25, v25 row_ror:8 row_mask:0xf bank_mask:0x3
	ds_read_b128 v[108:111], v9 offset:9920
	v_add_f32_dpp v52, v52, v52 row_mirror row_mask:0xf bank_mask:0xf bound_ctrl:1
	v_pk_fma_f32 v[6:7], v[46:47], v[52:53], v[56:57] op_sel_hi:[1,0,1]
	v_pk_fma_f32 v[26:27], v[4:5], v[100:101], v[26:27]
	v_pk_fma_f32 v[4:5], v[44:45], v[52:53], v[54:55] op_sel_hi:[1,0,1]
	ds_read_b128 v[96:99], v9 offset:9088
	v_add_f32_e32 v25, v26, v27
	v_pk_mul_f32 v[52:53], v[6:7], v[62:63]
	v_pk_mul_f32 v[56:57], v[6:7], v[66:67]
	v_pk_fma_f32 v[52:53], v[4:5], v[60:61], v[52:53]
	v_pk_mul_f32 v[54:55], v[4:5], v[64:65]
	v_add_f32_e32 v52, v52, v53
	ds_read_b128 v[12:15], v9 offset:11008
	ds_read_b128 v[16:19], v9 offset:10752
	v_add_f32_dpp v52, v52, v52 quad_perm:[1,0,3,2] row_mask:0xf bank_mask:0xf bound_ctrl:1
	v_pk_fma_f32 v[56:57], v[30:31], v[32:33], v[56:57] op_sel_hi:[1,0,1]
	v_pk_fma_f32 v[54:55], v[28:29], v[32:33], v[54:55] op_sel_hi:[1,0,1]
	v_add_f32_dpp v52, v52, v52 quad_perm:[2,3,0,1] row_mask:0xf bank_mask:0xf bound_ctrl:1
	ds_read_b128 v[20:23], v9 offset:11520
	ds_read_b32 v24, v10 offset:12032
	v_add_f32_dpp v52, v52, v52 row_half_mirror row_mask:0xf bank_mask:0xf bound_ctrl:1
	v_pk_mul_f32 v[26:27], v[6:7], v[38:39]
	v_add_f32_dpp v34, v25, v25 row_ror:8 row_mask:0xf bank_mask:0xc
	ds_read_b128 v[44:47], v9 offset:11264
	v_add_f32_dpp v52, v52, v52 row_mirror row_mask:0xf bank_mask:0xf bound_ctrl:1
	v_pk_fma_f32 v[6:7], v[50:51], v[52:53], v[56:57] op_sel_hi:[1,0,1]
	v_pk_fma_f32 v[26:27], v[4:5], v[36:37], v[26:27]
	v_pk_fma_f32 v[4:5], v[48:49], v[52:53], v[54:55] op_sel_hi:[1,0,1]
	ds_read_b128 v[100:103], v9 offset:10432
	v_add_f32_e32 v25, v26, v27
	v_add_f32_dpp v35, v34, v34 row_half_mirror row_mask:0xf bank_mask:0xa
	s_waitcnt lgkmcnt(6)
	v_pk_mul_f32 v[52:53], v[6:7], v[70:71]
	v_pk_mul_f32 v[56:57], v[6:7], v[74:75]
	v_pk_fma_f32 v[52:53], v[4:5], v[68:69], v[52:53]
	v_pk_mul_f32 v[54:55], v[4:5], v[72:73]
	v_add_f32_e32 v52, v52, v53
	ds_read_b128 v[60:63], v9 offset:12352
	ds_read_b128 v[64:67], v9 offset:12096
	v_add_f32_dpp v52, v52, v52 quad_perm:[1,0,3,2] row_mask:0xf bank_mask:0xf bound_ctrl:1
	v_pk_fma_f32 v[56:57], v[86:87], v[92:93], v[56:57] op_sel_hi:[1,0,1]
	v_pk_fma_f32 v[54:55], v[84:85], v[92:93], v[54:55] op_sel_hi:[1,0,1]
	v_add_f32_dpp v52, v52, v52 quad_perm:[2,3,0,1] row_mask:0xf bank_mask:0xf bound_ctrl:1
	ds_read_b128 v[28:31], v9 offset:12864
	ds_read_b32 v32, v10 offset:13376
	v_add_f32_dpp v52, v52, v52 row_half_mirror row_mask:0xf bank_mask:0xf bound_ctrl:1
	v_pk_mul_f32 v[26:27], v[6:7], v[42:43]
	v_add_f32_dpp v34, v25, v25 row_ror:8 row_mask:0xf bank_mask:0x3
	ds_read_b128 v[48:51], v9 offset:12608
	v_add_f32_dpp v52, v52, v52 row_mirror row_mask:0xf bank_mask:0xf bound_ctrl:1
	v_pk_fma_f32 v[6:7], v[106:107], v[52:53], v[56:57] op_sel_hi:[1,0,1]
	v_pk_fma_f32 v[26:27], v[4:5], v[40:41], v[26:27]
	v_pk_fma_f32 v[4:5], v[104:105], v[52:53], v[54:55] op_sel_hi:[1,0,1]
	ds_read_b128 v[36:39], v9 offset:11776
	v_add_f32_e32 v25, v26, v27
	v_pk_mul_f32 v[52:53], v[6:7], v[78:79]
	v_pk_mul_f32 v[56:57], v[6:7], v[82:83]
	v_pk_fma_f32 v[52:53], v[4:5], v[76:77], v[52:53]
	v_pk_mul_f32 v[54:55], v[4:5], v[80:81]
	v_add_f32_e32 v52, v52, v53
	ds_read_b128 v[68:71], v9 offset:13696
	ds_read_b128 v[72:75], v9 offset:13440
	v_add_f32_dpp v52, v52, v52 quad_perm:[1,0,3,2] row_mask:0xf bank_mask:0xf bound_ctrl:1
	v_pk_fma_f32 v[56:57], v[90:91], v[94:95], v[56:57] op_sel_hi:[1,0,1]
	v_pk_fma_f32 v[54:55], v[88:89], v[94:95], v[54:55] op_sel_hi:[1,0,1]
	v_add_f32_dpp v52, v52, v52 quad_perm:[2,3,0,1] row_mask:0xf bank_mask:0xf bound_ctrl:1
	ds_read_b128 v[84:87], v9 offset:14208
	ds_read_b32 v92, v10 offset:14720
	v_add_f32_dpp v52, v52, v52 row_half_mirror row_mask:0xf bank_mask:0xf bound_ctrl:1
	v_pk_mul_f32 v[26:27], v[6:7], v[98:99]
	v_add_f32_dpp v34, v25, v25 row_ror:8 row_mask:0xf bank_mask:0xc
	ds_read_b128 v[104:107], v9 offset:13952
	v_add_f32_dpp v52, v52, v52 row_mirror row_mask:0xf bank_mask:0xf bound_ctrl:1
	v_pk_fma_f32 v[6:7], v[110:111], v[52:53], v[56:57] op_sel_hi:[1,0,1]
	v_pk_fma_f32 v[26:27], v[4:5], v[96:97], v[26:27]
	v_pk_fma_f32 v[4:5], v[108:109], v[52:53], v[54:55] op_sel_hi:[1,0,1]
	ds_read_b128 v[40:43], v9 offset:13120
	v_add_f32_e32 v25, v26, v27
	v_add_f32_dpp v58, v34, v34 row_half_mirror row_mask:0xf bank_mask:0x5
	s_waitcnt lgkmcnt(6)
; __device__ void scan_block(const Params& P, int sb, unsigned char* lds) {
;     ...
;       for (int s = 0; s < SC_CH; ++s) {
;         f32x4 w4n, k4n, b4n, kh4n, r4n; float vn;
;         if (s + 1 < SC_CH) {
;           const float* qn = q + (s + 1) * SC_STEP;
;           w4n = *(const f32x4*)(qn); k4n = *(const f32x4*)(qn + 64); b4n = *(const f32x4*)(qn + 128); kh4n = *(const f32x4*)(qn + 192); r4n = *(const f32x4*)(qn + 256);
;           vn = qv[(s + 1) * SC_STEP];
;         }
;         __builtin_amdgcn_sched_barrier(0);
;         if (s > 0) {
;           const float y = dpp_allreduce16(ypart);
;           yk = (ks == ((s - 1) & 15)) ? y : yk;
;           if (((s - 1) & 15) == 15) yo[(size_t)(s - 16) * 1024] = yk;
;         }
;         const f32x2 pp = (f32x2){S[0], S[1]} * (f32x2){k4[0], k4[1]} + (f32x2){S[2], S[3]} * (f32x2){k4[2], k4[3]};
;         const f32x4 A = S * w4 + v * kh4;
;         const float ar = dpp_allreduce16(pp.x + pp.y);
;         S = A + ar * b4;
;         const f32x2 yy = (f32x2){S[0], S[1]} * (f32x2){r4[0], r4[1]} + (f32x2){S[2], S[3]} * (f32x2){r4[2], r4[3]};
;         ypart = yy.x + yy.y;
;         if (s + 1 < SC_CH) { w4 = w4n; k4 = k4n; b4 = b4n; kh4 = kh4n; r4 = r4n; v = vn; }
;       }
	v_pk_mul_f32 v[52:53], v[6:7], v[14:15]
	v_pk_mul_f32 v[56:57], v[6:7], v[18:19]
	v_pk_fma_f32 v[52:53], v[4:5], v[12:13], v[52:53]
	v_pk_mul_f32 v[54:55], v[4:5], v[16:17]
	v_add_f32_e32 v52, v52, v53
	ds_read_b128 v[76:79], v9 offset:15040
	ds_read_b128 v[80:83], v9 offset:14784
	v_add_f32_dpp v52, v52, v52 quad_perm:[1,0,3,2] row_mask:0xf bank_mask:0xf bound_ctrl:1
	v_pk_fma_f32 v[56:57], v[22:23], v[24:25], v[56:57] op_sel_hi:[1,0,1]
	v_pk_fma_f32 v[54:55], v[20:21], v[24:25], v[54:55] op_sel_hi:[1,0,1]
	v_add_f32_dpp v52, v52, v52 quad_perm:[2,3,0,1] row_mask:0xf bank_mask:0xf bound_ctrl:1
	ds_read_b128 v[88:91], v9 offset:15552
	ds_read_b32 v94, v10 offset:16064
	v_add_f32_dpp v52, v52, v52 row_half_mirror row_mask:0xf bank_mask:0xf bound_ctrl:1
	v_pk_mul_f32 v[26:27], v[6:7], v[102:103]
	v_add_f32_dpp v34, v25, v25 row_ror:8 row_mask:0xf bank_mask:0x3
	ds_read_b128 v[108:111], v9 offset:15296
	v_add_f32_dpp v52, v52, v52 row_mirror row_mask:0xf bank_mask:0xf bound_ctrl:1
	v_pk_fma_f32 v[6:7], v[46:47], v[52:53], v[56:57] op_sel_hi:[1,0,1]
	v_pk_fma_f32 v[26:27], v[4:5], v[100:101], v[26:27]
	v_pk_fma_f32 v[4:5], v[44:45], v[52:53], v[54:55] op_sel_hi:[1,0,1]
	ds_read_b128 v[96:99], v9 offset:14464
	v_add_f32_e32 v25, v26, v27
	v_pk_mul_f32 v[52:53], v[6:7], v[62:63]
	v_pk_mul_f32 v[56:57], v[6:7], v[66:67]
	v_pk_fma_f32 v[52:53], v[4:5], v[60:61], v[52:53]
	v_pk_mul_f32 v[54:55], v[4:5], v[64:65]
	v_add_f32_e32 v52, v52, v53
	ds_read_b128 v[12:15], v9 offset:16384
	ds_read_b128 v[16:19], v9 offset:16128
	v_add_f32_dpp v52, v52, v52 quad_perm:[1,0,3,2] row_mask:0xf bank_mask:0xf bound_ctrl:1
	v_pk_fma_f32 v[56:57], v[30:31], v[32:33], v[56:57] op_sel_hi:[1,0,1]
	v_pk_fma_f32 v[54:55], v[28:29], v[32:33], v[54:55] op_sel_hi:[1,0,1]
	v_add_f32_dpp v52, v52, v52 quad_perm:[2,3,0,1] row_mask:0xf bank_mask:0xf bound_ctrl:1
	ds_read_b128 v[20:23], v9 offset:16896
	ds_read_b32 v24, v10 offset:17408
	v_add_f32_dpp v52, v52, v52 row_half_mirror row_mask:0xf bank_mask:0xf bound_ctrl:1
	v_pk_mul_f32 v[26:27], v[6:7], v[38:39]
	v_add_f32_dpp v34, v25, v25 row_ror:8 row_mask:0xf bank_mask:0xc
	ds_read_b128 v[44:47], v9 offset:16640
	v_add_f32_dpp v52, v52, v52 row_mirror row_mask:0xf bank_mask:0xf bound_ctrl:1
	v_pk_fma_f32 v[6:7], v[50:51], v[52:53], v[56:57] op_sel_hi:[1,0,1]
	v_pk_fma_f32 v[26:27], v[4:5], v[36:37], v[26:27]
	v_pk_fma_f32 v[4:5], v[48:49], v[52:53], v[54:55] op_sel_hi:[1,0,1]
	ds_read_b128 v[100:103], v9 offset:15808
	v_add_f32_e32 v25, v26, v27
	v_add_f32_dpp v58, v34, v34 row_half_mirror row_mask:0xf bank_mask:0xa
	s_waitcnt lgkmcnt(6)
	v_pk_mul_f32 v[52:53], v[6:7], v[70:71]
	v_pk_mul_f32 v[56:57], v[6:7], v[74:75]
	v_pk_fma_f32 v[52:53], v[4:5], v[68:69], v[52:53]
	v_pk_mul_f32 v[54:55], v[4:5], v[72:73]
	v_add_f32_e32 v52, v52, v53
	ds_read_b128 v[60:63], v9 offset:17728
	ds_read_b128 v[64:67], v9 offset:17472
	v_add_f32_dpp v52, v52, v52 quad_perm:[1,0,3,2] row_mask:0xf bank_mask:0xf bound_ctrl:1
	v_pk_fma_f32 v[56:57], v[86:87], v[92:93], v[56:57] op_sel_hi:[1,0,1]
	v_pk_fma_f32 v[54:55], v[84:85], v[92:93], v[54:55] op_sel_hi:[1,0,1]
	v_cndmask_b32_e64 v255, v35, v58, s[40:41]
	v_add_f32_dpp v52, v52, v52 quad_perm:[2,3,0,1] row_mask:0xf bank_mask:0xf bound_ctrl:1
	ds_read_b128 v[28:31], v9 offset:18240
	ds_read_b32 v32, v10 offset:18752
	v_add_f32_dpp v52, v52, v52 row_half_mirror row_mask:0xf bank_mask:0xf bound_ctrl:1
	v_pk_mul_f32 v[26:27], v[6:7], v[42:43]
	v_add_f32_dpp v34, v25, v25 row_ror:8 row_mask:0xf bank_mask:0x3
	ds_read_b128 v[48:51], v9 offset:17984
	v_add_f32_dpp v52, v52, v52 row_mirror row_mask:0xf bank_mask:0xf bound_ctrl:1
	v_pk_fma_f32 v[6:7], v[106:107], v[52:53], v[56:57] op_sel_hi:[1,0,1]
	v_pk_fma_f32 v[26:27], v[4:5], v[40:41], v[26:27]
	v_pk_fma_f32 v[4:5], v[104:105], v[52:53], v[54:55] op_sel_hi:[1,0,1]
	ds_read_b128 v[36:39], v9 offset:17152
	v_add_f32_e32 v25, v26, v27
	v_pk_mul_f32 v[52:53], v[6:7], v[78:79]
	v_pk_mul_f32 v[56:57], v[6:7], v[82:83]
	v_pk_fma_f32 v[52:53], v[4:5], v[76:77], v[52:53]
	v_pk_mul_f32 v[54:55], v[4:5], v[80:81]
	v_add_f32_e32 v52, v52, v53
	ds_read_b128 v[68:71], v9 offset:19072
	ds_read_b128 v[72:75], v9 offset:18816
	v_add_f32_dpp v52, v52, v52 quad_perm:[1,0,3,2] row_mask:0xf bank_mask:0xf bound_ctrl:1
	v_pk_fma_f32 v[56:57], v[90:91], v[94:95], v[56:57] op_sel_hi:[1,0,1]
	v_pk_fma_f32 v[54:55], v[88:89], v[94:95], v[54:55] op_sel_hi:[1,0,1]
	v_add_f32_dpp v52, v52, v52 quad_perm:[2,3,0,1] row_mask:0xf bank_mask:0xf bound_ctrl:1
	ds_read_b128 v[84:87], v9 offset:19584
	ds_read_b32 v92, v10 offset:20096
	v_add_f32_dpp v52, v52, v52 row_half_mirror row_mask:0xf bank_mask:0xf bound_ctrl:1
	v_pk_mul_f32 v[26:27], v[6:7], v[98:99]
	v_add_f32_dpp v34, v25, v25 row_ror:8 row_mask:0xf bank_mask:0xc
	ds_read_b128 v[104:107], v9 offset:19328
	v_add_f32_dpp v52, v52, v52 row_mirror row_mask:0xf bank_mask:0xf bound_ctrl:1
	v_pk_fma_f32 v[6:7], v[110:111], v[52:53], v[56:57] op_sel_hi:[1,0,1]
	v_pk_fma_f32 v[26:27], v[4:5], v[96:97], v[26:27]
	v_pk_fma_f32 v[4:5], v[108:109], v[52:53], v[54:55] op_sel_hi:[1,0,1]
	ds_read_b128 v[40:43], v9 offset:18496
	v_add_f32_e32 v25, v26, v27
	v_add_f32_dpp v0, v34, v34 row_half_mirror row_mask:0xf bank_mask:0x5
	s_waitcnt lgkmcnt(6)
; __device__ void scan_block(const Params& P, int sb, unsigned char* lds) {
;     ...
;       for (int s = 0; s < SC_CH; ++s) {
;         f32x4 w4n, k4n, b4n, kh4n, r4n; float vn;
;         if (s + 1 < SC_CH) {
;           const float* qn = q + (s + 1) * SC_STEP;
;           w4n = *(const f32x4*)(qn); k4n = *(const f32x4*)(qn + 64); b4n = *(const f32x4*)(qn + 128); kh4n = *(const f32x4*)(qn + 192); r4n = *(const f32x4*)(qn + 256);
;           vn = qv[(s + 1) * SC_STEP];
;         }
;         __builtin_amdgcn_sched_barrier(0);
;         if (s > 0) {
;           const float y = dpp_allreduce16(ypart);
;           yk = (ks == ((s - 1) & 15)) ? y : yk;
;           if (((s - 1) & 15) == 15) yo[(size_t)(s - 16) * 1024] = yk;
;         }
;         const f32x2 pp = (f32x2){S[0], S[1]} * (f32x2){k4[0], k4[1]} + (f32x2){S[2], S[3]} * (f32x2){k4[2], k4[3]};
;         const f32x4 A = S * w4 + v * kh4;
;         const float ar = dpp_allreduce16(pp.x + pp.y);
;         S = A + ar * b4;
;         const f32x2 yy = (f32x2){S[0], S[1]} * (f32x2){r4[0], r4[1]} + (f32x2){S[2], S[3]} * (f32x2){r4[2], r4[3]};
;         ypart = yy.x + yy.y;
;         if (s + 1 < SC_CH) { w4 = w4n; k4 = k4n; b4 = b4n; kh4 = kh4n; r4 = r4n; v = vn; }
;       }
	v_pk_mul_f32 v[52:53], v[6:7], v[14:15]
	v_pk_mul_f32 v[56:57], v[6:7], v[18:19]
	v_pk_fma_f32 v[52:53], v[4:5], v[12:13], v[52:53]
	v_pk_mul_f32 v[54:55], v[4:5], v[16:17]
	v_add_f32_e32 v52, v52, v53
	ds_read_b128 v[76:79], v9 offset:20416
	ds_read_b128 v[80:83], v9 offset:20160
	v_add_f32_dpp v52, v52, v52 quad_perm:[1,0,3,2] row_mask:0xf bank_mask:0xf bound_ctrl:1
	v_pk_fma_f32 v[56:57], v[22:23], v[24:25], v[56:57] op_sel_hi:[1,0,1]
	v_pk_fma_f32 v[54:55], v[20:21], v[24:25], v[54:55] op_sel_hi:[1,0,1]
	v_cndmask_b32_e64 v8, v58, v35, s[40:41]
	v_add_f32_dpp v52, v52, v52 quad_perm:[2,3,0,1] row_mask:0xf bank_mask:0xf bound_ctrl:1
	ds_read_b128 v[88:91], v9 offset:20928
	ds_read_b32 v94, v10 offset:21440
	v_add_f32_dpp v52, v52, v52 row_half_mirror row_mask:0xf bank_mask:0xf bound_ctrl:1
	v_pk_mul_f32 v[26:27], v[6:7], v[102:103]
	v_add_f32_dpp v34, v25, v25 row_ror:8 row_mask:0xf bank_mask:0x3
	ds_read_b128 v[108:111], v9 offset:20672
	v_add_f32_dpp v52, v52, v52 row_mirror row_mask:0xf bank_mask:0xf bound_ctrl:1
	v_pk_fma_f32 v[6:7], v[46:47], v[52:53], v[56:57] op_sel_hi:[1,0,1]
	v_pk_fma_f32 v[26:27], v[4:5], v[100:101], v[26:27]
	v_pk_fma_f32 v[4:5], v[44:45], v[52:53], v[54:55] op_sel_hi:[1,0,1]
	ds_read_b128 v[96:99], v9 offset:19840
	v_add_f32_e32 v25, v26, v27
	v_pk_mul_f32 v[52:53], v[6:7], v[62:63]
	v_pk_mul_f32 v[56:57], v[6:7], v[66:67]
	v_pk_fma_f32 v[52:53], v[4:5], v[60:61], v[52:53]
	v_pk_mul_f32 v[54:55], v[4:5], v[64:65]
	v_add_f32_e32 v52, v52, v53
	ds_read_b128 v[12:15], v9 offset:21760
	ds_read_b128 v[16:19], v9 offset:21504
	v_add_f32_dpp v52, v52, v52 quad_perm:[1,0,3,2] row_mask:0xf bank_mask:0xf bound_ctrl:1
	v_pk_fma_f32 v[56:57], v[30:31], v[32:33], v[56:57] op_sel_hi:[1,0,1]
	v_pk_fma_f32 v[54:55], v[28:29], v[32:33], v[54:55] op_sel_hi:[1,0,1]
	v_add_f32_dpp v52, v52, v52 quad_perm:[2,3,0,1] row_mask:0xf bank_mask:0xf bound_ctrl:1
	ds_read_b128 v[20:23], v9 offset:22272
	ds_read_b32 v24, v10 offset:22784
	v_add_f32_dpp v52, v52, v52 row_half_mirror row_mask:0xf bank_mask:0xf bound_ctrl:1
	v_pk_mul_f32 v[26:27], v[6:7], v[38:39]
	v_add_f32_dpp v34, v25, v25 row_ror:8 row_mask:0xf bank_mask:0xc
	ds_read_b128 v[44:47], v9 offset:22016
	v_add_f32_dpp v52, v52, v52 row_mirror row_mask:0xf bank_mask:0xf bound_ctrl:1
	v_pk_fma_f32 v[6:7], v[50:51], v[52:53], v[56:57] op_sel_hi:[1,0,1]
	v_pk_fma_f32 v[26:27], v[4:5], v[36:37], v[26:27]
	v_pk_fma_f32 v[4:5], v[48:49], v[52:53], v[54:55] op_sel_hi:[1,0,1]
	ds_read_b128 v[100:103], v9 offset:21184
	v_add_f32_e32 v25, v26, v27
	v_add_f32_dpp v0, v34, v34 row_half_mirror row_mask:0xf bank_mask:0xa
	s_waitcnt lgkmcnt(6)
	v_pk_mul_f32 v[52:53], v[6:7], v[70:71]
	v_pk_mul_f32 v[56:57], v[6:7], v[74:75]
	v_pk_fma_f32 v[52:53], v[4:5], v[68:69], v[52:53]
	v_pk_mul_f32 v[54:55], v[4:5], v[72:73]
	v_add_f32_e32 v52, v52, v53
	ds_read_b128 v[60:63], v9 offset:23104
	ds_read_b128 v[64:67], v9 offset:22848
	v_add_f32_dpp v52, v52, v52 quad_perm:[1,0,3,2] row_mask:0xf bank_mask:0xf bound_ctrl:1
	v_pk_fma_f32 v[56:57], v[86:87], v[92:93], v[56:57] op_sel_hi:[1,0,1]
	v_pk_fma_f32 v[54:55], v[84:85], v[92:93], v[54:55] op_sel_hi:[1,0,1]
	v_add_f32_dpp v253, v8, v255 quad_perm:[2,3,0,1] row_mask:0xf bank_mask:0xf bound_ctrl:1
	v_add_f32_dpp v52, v52, v52 quad_perm:[2,3,0,1] row_mask:0xf bank_mask:0xf bound_ctrl:1
	ds_read_b128 v[28:31], v9 offset:23616
	ds_read_b32 v32, v10 offset:24128
	v_add_f32_dpp v52, v52, v52 row_half_mirror row_mask:0xf bank_mask:0xf bound_ctrl:1
	v_pk_mul_f32 v[26:27], v[6:7], v[42:43]
	v_add_f32_dpp v34, v25, v25 row_ror:8 row_mask:0xf bank_mask:0x3
	ds_read_b128 v[48:51], v9 offset:23360
	v_add_f32_dpp v52, v52, v52 row_mirror row_mask:0xf bank_mask:0xf bound_ctrl:1
	v_pk_fma_f32 v[6:7], v[106:107], v[52:53], v[56:57] op_sel_hi:[1,0,1]
	v_pk_fma_f32 v[26:27], v[4:5], v[40:41], v[26:27]
	v_pk_fma_f32 v[4:5], v[104:105], v[52:53], v[54:55] op_sel_hi:[1,0,1]
	ds_read_b128 v[36:39], v9 offset:22528
	v_add_f32_e32 v25, v26, v27
	v_pk_mul_f32 v[52:53], v[6:7], v[78:79]
	v_pk_mul_f32 v[56:57], v[6:7], v[82:83]
	v_pk_fma_f32 v[52:53], v[4:5], v[76:77], v[52:53]
	v_pk_mul_f32 v[54:55], v[4:5], v[80:81]
	v_add_f32_e32 v52, v52, v53
	ds_read_b128 v[68:71], v9 offset:24448
	ds_read_b128 v[72:75], v9 offset:24192
	v_add_f32_dpp v52, v52, v52 quad_perm:[1,0,3,2] row_mask:0xf bank_mask:0xf bound_ctrl:1
	v_pk_fma_f32 v[56:57], v[90:91], v[94:95], v[56:57] op_sel_hi:[1,0,1]
	v_pk_fma_f32 v[54:55], v[88:89], v[94:95], v[54:55] op_sel_hi:[1,0,1]
	v_add_f32_dpp v52, v52, v52 quad_perm:[2,3,0,1] row_mask:0xf bank_mask:0xf bound_ctrl:1
	ds_read_b128 v[84:87], v9 offset:24960
	ds_read_b32 v92, v10 offset:25472
	v_add_f32_dpp v52, v52, v52 row_half_mirror row_mask:0xf bank_mask:0xf bound_ctrl:1
	v_pk_mul_f32 v[26:27], v[6:7], v[98:99]
	v_add_f32_dpp v34, v25, v25 row_ror:8 row_mask:0xf bank_mask:0xc
	ds_read_b128 v[104:107], v9 offset:24704
	v_add_f32_dpp v52, v52, v52 row_mirror row_mask:0xf bank_mask:0xf bound_ctrl:1
	v_pk_fma_f32 v[6:7], v[110:111], v[52:53], v[56:57] op_sel_hi:[1,0,1]
	v_pk_fma_f32 v[26:27], v[4:5], v[96:97], v[26:27]
	v_pk_fma_f32 v[4:5], v[108:109], v[52:53], v[54:55] op_sel_hi:[1,0,1]
	ds_read_b128 v[40:43], v9 offset:23872
	v_add_f32_e32 v25, v26, v27
	v_add_f32_dpp v11, v34, v34 row_half_mirror row_mask:0xf bank_mask:0x5
	s_waitcnt lgkmcnt(6)
; __device__ void scan_block(const Params& P, int sb, unsigned char* lds) {
;     ...
;       for (int s = 0; s < SC_CH; ++s) {
;         f32x4 w4n, k4n, b4n, kh4n, r4n; float vn;
;         if (s + 1 < SC_CH) {
;           const float* qn = q + (s + 1) * SC_STEP;
;           w4n = *(const f32x4*)(qn); k4n = *(const f32x4*)(qn + 64); b4n = *(const f32x4*)(qn + 128); kh4n = *(const f32x4*)(qn + 192); r4n = *(const f32x4*)(qn + 256);
;           vn = qv[(s + 1) * SC_STEP];
;         }
;         __builtin_amdgcn_sched_barrier(0);
;         if (s > 0) {
;           const float y = dpp_allreduce16(ypart);
;           yk = (ks == ((s - 1) & 15)) ? y : yk;
;           if (((s - 1) & 15) == 15) yo[(size_t)(s - 16) * 1024] = yk;
;         }
;         const f32x2 pp = (f32x2){S[0], S[1]} * (f32x2){k4[0], k4[1]} + (f32x2){S[2], S[3]} * (f32x2){k4[2], k4[3]};
;         const f32x4 A = S * w4 + v * kh4;
;         const float ar = dpp_allreduce16(pp.x + pp.y);
;         S = A + ar * b4;
;         const f32x2 yy = (f32x2){S[0], S[1]} * (f32x2){r4[0], r4[1]} + (f32x2){S[2], S[3]} * (f32x2){r4[2], r4[3]};
;         ypart = yy.x + yy.y;
;         if (s + 1 < SC_CH) { w4 = w4n; k4 = k4n; b4 = b4n; kh4 = kh4n; r4 = r4n; v = vn; }
;       }
	v_pk_mul_f32 v[52:53], v[6:7], v[14:15]
	v_pk_mul_f32 v[56:57], v[6:7], v[18:19]
	v_pk_fma_f32 v[52:53], v[4:5], v[12:13], v[52:53]
	v_pk_mul_f32 v[54:55], v[4:5], v[16:17]
	v_add_f32_e32 v52, v52, v53
	ds_read_b128 v[76:79], v9 offset:25792
	ds_read_b128 v[80:83], v9 offset:25536
	v_add_f32_dpp v52, v52, v52 quad_perm:[1,0,3,2] row_mask:0xf bank_mask:0xf bound_ctrl:1
	v_pk_fma_f32 v[56:57], v[22:23], v[24:25], v[56:57] op_sel_hi:[1,0,1]
	v_pk_fma_f32 v[54:55], v[20:21], v[24:25], v[54:55] op_sel_hi:[1,0,1]
	v_add_f32_dpp v52, v52, v52 quad_perm:[2,3,0,1] row_mask:0xf bank_mask:0xf bound_ctrl:1
	ds_read_b128 v[88:91], v9 offset:26304
	ds_read_b32 v94, v10 offset:26816
	v_add_f32_dpp v52, v52, v52 row_half_mirror row_mask:0xf bank_mask:0xf bound_ctrl:1
	v_pk_mul_f32 v[26:27], v[6:7], v[102:103]
	v_add_f32_dpp v34, v25, v25 row_ror:8 row_mask:0xf bank_mask:0x3
	ds_read_b128 v[108:111], v9 offset:26048
	v_add_f32_dpp v52, v52, v52 row_mirror row_mask:0xf bank_mask:0xf bound_ctrl:1
	v_pk_fma_f32 v[6:7], v[46:47], v[52:53], v[56:57] op_sel_hi:[1,0,1]
	v_pk_fma_f32 v[26:27], v[4:5], v[100:101], v[26:27]
	v_pk_fma_f32 v[4:5], v[44:45], v[52:53], v[54:55] op_sel_hi:[1,0,1]
	ds_read_b128 v[96:99], v9 offset:25216
	v_add_f32_e32 v25, v26, v27
	v_pk_mul_f32 v[52:53], v[6:7], v[62:63]
	v_pk_mul_f32 v[56:57], v[6:7], v[66:67]
	v_pk_fma_f32 v[52:53], v[4:5], v[60:61], v[52:53]
	v_pk_mul_f32 v[54:55], v[4:5], v[64:65]
	v_add_f32_e32 v52, v52, v53
	ds_read_b128 v[12:15], v9 offset:27136
	ds_read_b128 v[16:19], v9 offset:26880
	v_add_f32_dpp v52, v52, v52 quad_perm:[1,0,3,2] row_mask:0xf bank_mask:0xf bound_ctrl:1
	v_pk_fma_f32 v[56:57], v[30:31], v[32:33], v[56:57] op_sel_hi:[1,0,1]
	v_pk_fma_f32 v[54:55], v[28:29], v[32:33], v[54:55] op_sel_hi:[1,0,1]
	v_add_f32_dpp v52, v52, v52 quad_perm:[2,3,0,1] row_mask:0xf bank_mask:0xf bound_ctrl:1
	ds_read_b128 v[20:23], v9 offset:27648
	ds_read_b32 v24, v10 offset:28160
	v_add_f32_dpp v52, v52, v52 row_half_mirror row_mask:0xf bank_mask:0xf bound_ctrl:1
	v_pk_mul_f32 v[26:27], v[6:7], v[38:39]
	v_add_f32_dpp v34, v25, v25 row_ror:8 row_mask:0xf bank_mask:0xc
	ds_read_b128 v[44:47], v9 offset:27392
	v_add_f32_dpp v52, v52, v52 row_mirror row_mask:0xf bank_mask:0xf bound_ctrl:1
	v_pk_fma_f32 v[6:7], v[50:51], v[52:53], v[56:57] op_sel_hi:[1,0,1]
	v_pk_fma_f32 v[26:27], v[4:5], v[36:37], v[26:27]
	v_pk_fma_f32 v[4:5], v[48:49], v[52:53], v[54:55] op_sel_hi:[1,0,1]
	ds_read_b128 v[100:103], v9 offset:26560
	v_add_f32_e32 v25, v26, v27
	v_add_f32_dpp v11, v34, v34 row_half_mirror row_mask:0xf bank_mask:0xa
	s_waitcnt lgkmcnt(6)
	v_pk_mul_f32 v[52:53], v[6:7], v[70:71]
	v_pk_mul_f32 v[56:57], v[6:7], v[74:75]
	v_pk_fma_f32 v[52:53], v[4:5], v[68:69], v[52:53]
	v_pk_mul_f32 v[54:55], v[4:5], v[72:73]
	v_add_f32_e32 v52, v52, v53
	ds_read_b128 v[60:63], v9 offset:28480
	ds_read_b128 v[64:67], v9 offset:28224
	v_add_f32_dpp v52, v52, v52 quad_perm:[1,0,3,2] row_mask:0xf bank_mask:0xf bound_ctrl:1
	v_pk_fma_f32 v[56:57], v[86:87], v[92:93], v[56:57] op_sel_hi:[1,0,1]
	v_pk_fma_f32 v[54:55], v[84:85], v[92:93], v[54:55] op_sel_hi:[1,0,1]
	v_cndmask_b32_e64 v255, v0, v11, s[40:41]
	v_add_f32_dpp v52, v52, v52 quad_perm:[2,3,0,1] row_mask:0xf bank_mask:0xf bound_ctrl:1
	ds_read_b128 v[28:31], v9 offset:28992
	ds_read_b32 v32, v10 offset:29504
	v_add_f32_dpp v52, v52, v52 row_half_mirror row_mask:0xf bank_mask:0xf bound_ctrl:1
	v_pk_mul_f32 v[26:27], v[6:7], v[42:43]
	v_add_f32_dpp v34, v25, v25 row_ror:8 row_mask:0xf bank_mask:0x3
	ds_read_b128 v[48:51], v9 offset:28736
	v_add_f32_dpp v52, v52, v52 row_mirror row_mask:0xf bank_mask:0xf bound_ctrl:1
	v_pk_fma_f32 v[6:7], v[106:107], v[52:53], v[56:57] op_sel_hi:[1,0,1]
	v_pk_fma_f32 v[26:27], v[4:5], v[40:41], v[26:27]
	v_pk_fma_f32 v[4:5], v[104:105], v[52:53], v[54:55] op_sel_hi:[1,0,1]
	ds_read_b128 v[36:39], v9 offset:27904
	v_add_f32_e32 v25, v26, v27
	v_pk_mul_f32 v[52:53], v[6:7], v[78:79]
	v_pk_mul_f32 v[56:57], v[6:7], v[82:83]
	v_pk_fma_f32 v[52:53], v[4:5], v[76:77], v[52:53]
	v_pk_mul_f32 v[54:55], v[4:5], v[80:81]
	v_add_f32_e32 v52, v52, v53
	ds_read_b128 v[68:71], v9 offset:29824
	ds_read_b128 v[72:75], v9 offset:29568
	v_add_f32_dpp v52, v52, v52 quad_perm:[1,0,3,2] row_mask:0xf bank_mask:0xf bound_ctrl:1
	v_pk_fma_f32 v[56:57], v[90:91], v[94:95], v[56:57] op_sel_hi:[1,0,1]
	v_pk_fma_f32 v[54:55], v[88:89], v[94:95], v[54:55] op_sel_hi:[1,0,1]
	v_add_f32_dpp v52, v52, v52 quad_perm:[2,3,0,1] row_mask:0xf bank_mask:0xf bound_ctrl:1
	ds_read_b128 v[84:87], v9 offset:30336
	ds_read_b32 v92, v10 offset:30848
	v_add_f32_dpp v52, v52, v52 row_half_mirror row_mask:0xf bank_mask:0xf bound_ctrl:1
	v_pk_mul_f32 v[26:27], v[6:7], v[98:99]
	v_add_f32_dpp v34, v25, v25 row_ror:8 row_mask:0xf bank_mask:0xc
	ds_read_b128 v[104:107], v9 offset:30080
	v_add_f32_dpp v52, v52, v52 row_mirror row_mask:0xf bank_mask:0xf bound_ctrl:1
	v_pk_fma_f32 v[6:7], v[110:111], v[52:53], v[56:57] op_sel_hi:[1,0,1]
	v_pk_fma_f32 v[26:27], v[4:5], v[96:97], v[26:27]
	v_pk_fma_f32 v[4:5], v[108:109], v[52:53], v[54:55] op_sel_hi:[1,0,1]
	ds_read_b128 v[40:43], v9 offset:29248
	v_add_f32_e32 v25, v26, v27
	v_add_f32_dpp v35, v34, v34 row_half_mirror row_mask:0xf bank_mask:0x5
	s_waitcnt lgkmcnt(6)
; __device__ void scan_block(const Params& P, int sb, unsigned char* lds) {
;     ...
;       for (int s = 0; s < SC_CH; ++s) {
;         f32x4 w4n, k4n, b4n, kh4n, r4n; float vn;
;         if (s + 1 < SC_CH) {
;           const float* qn = q + (s + 1) * SC_STEP;
;           w4n = *(const f32x4*)(qn); k4n = *(const f32x4*)(qn + 64); b4n = *(const f32x4*)(qn + 128); kh4n = *(const f32x4*)(qn + 192); r4n = *(const f32x4*)(qn + 256);
;           vn = qv[(s + 1) * SC_STEP];
;         }
;         __builtin_amdgcn_sched_barrier(0);
;         if (s > 0) {
;           const float y = dpp_allreduce16(ypart);
;           yk = (ks == ((s - 1) & 15)) ? y : yk;
;           if (((s - 1) & 15) == 15) yo[(size_t)(s - 16) * 1024] = yk;
;         }
;         const f32x2 pp = (f32x2){S[0], S[1]} * (f32x2){k4[0], k4[1]} + (f32x2){S[2], S[3]} * (f32x2){k4[2], k4[3]};
;         const f32x4 A = S * w4 + v * kh4;
;         const float ar = dpp_allreduce16(pp.x + pp.y);
;         S = A + ar * b4;
;         const f32x2 yy = (f32x2){S[0], S[1]} * (f32x2){r4[0], r4[1]} + (f32x2){S[2], S[3]} * (f32x2){r4[2], r4[3]};
;         ypart = yy.x + yy.y;
;         if (s + 1 < SC_CH) { w4 = w4n; k4 = k4n; b4 = b4n; kh4 = kh4n; r4 = r4n; v = vn; }
;       }
	v_pk_mul_f32 v[52:53], v[6:7], v[14:15]
	v_pk_mul_f32 v[56:57], v[6:7], v[18:19]
	v_pk_fma_f32 v[52:53], v[4:5], v[12:13], v[52:53]
	v_pk_mul_f32 v[54:55], v[4:5], v[16:17]
	v_add_f32_e32 v52, v52, v53
	ds_read_b128 v[76:79], v9 offset:31168
	ds_read_b128 v[80:83], v9 offset:30912
	v_add_f32_dpp v52, v52, v52 quad_perm:[1,0,3,2] row_mask:0xf bank_mask:0xf bound_ctrl:1
	v_pk_fma_f32 v[56:57], v[22:23], v[24:25], v[56:57] op_sel_hi:[1,0,1]
	v_pk_fma_f32 v[54:55], v[20:21], v[24:25], v[54:55] op_sel_hi:[1,0,1]
	v_cndmask_b32_e64 v8, v11, v0, s[40:41]
	v_add_f32_dpp v52, v52, v52 quad_perm:[2,3,0,1] row_mask:0xf bank_mask:0xf bound_ctrl:1
	ds_read_b128 v[88:91], v9 offset:31680
	ds_read_b32 v94, v10 offset:32192
	v_add_f32_dpp v52, v52, v52 row_half_mirror row_mask:0xf bank_mask:0xf bound_ctrl:1
	v_pk_mul_f32 v[26:27], v[6:7], v[102:103]
	v_add_f32_dpp v34, v25, v25 row_ror:8 row_mask:0xf bank_mask:0x3
	ds_read_b128 v[108:111], v9 offset:31424
	v_add_f32_dpp v52, v52, v52 row_mirror row_mask:0xf bank_mask:0xf bound_ctrl:1
	v_pk_fma_f32 v[6:7], v[46:47], v[52:53], v[56:57] op_sel_hi:[1,0,1]
	v_pk_fma_f32 v[26:27], v[4:5], v[100:101], v[26:27]
	v_pk_fma_f32 v[4:5], v[44:45], v[52:53], v[54:55] op_sel_hi:[1,0,1]
	ds_read_b128 v[96:99], v9 offset:30592
	v_add_f32_e32 v25, v26, v27
	v_pk_mul_f32 v[52:53], v[6:7], v[62:63]
	v_pk_mul_f32 v[56:57], v[6:7], v[66:67]
	v_pk_fma_f32 v[52:53], v[4:5], v[60:61], v[52:53]
	v_pk_mul_f32 v[54:55], v[4:5], v[64:65]
	v_add_f32_e32 v52, v52, v53
	ds_read_b128 v[12:15], v9 offset:32512
	ds_read_b128 v[16:19], v9 offset:32256
	v_add_f32_dpp v52, v52, v52 quad_perm:[1,0,3,2] row_mask:0xf bank_mask:0xf bound_ctrl:1
	v_pk_fma_f32 v[56:57], v[30:31], v[32:33], v[56:57] op_sel_hi:[1,0,1]
	v_pk_fma_f32 v[54:55], v[28:29], v[32:33], v[54:55] op_sel_hi:[1,0,1]
	v_add_f32_dpp v52, v52, v52 quad_perm:[2,3,0,1] row_mask:0xf bank_mask:0xf bound_ctrl:1
	ds_read_b128 v[20:23], v9 offset:33024
	ds_read_b32 v24, v10 offset:33536
	v_add_f32_dpp v52, v52, v52 row_half_mirror row_mask:0xf bank_mask:0xf bound_ctrl:1
	v_pk_mul_f32 v[26:27], v[6:7], v[38:39]
	v_add_f32_dpp v34, v25, v25 row_ror:8 row_mask:0xf bank_mask:0xc
	ds_read_b128 v[44:47], v9 offset:32768
	v_add_f32_dpp v52, v52, v52 row_mirror row_mask:0xf bank_mask:0xf bound_ctrl:1
	v_pk_fma_f32 v[6:7], v[50:51], v[52:53], v[56:57] op_sel_hi:[1,0,1]
	v_pk_fma_f32 v[26:27], v[4:5], v[36:37], v[26:27]
	v_pk_fma_f32 v[4:5], v[48:49], v[52:53], v[54:55] op_sel_hi:[1,0,1]
	ds_read_b128 v[100:103], v9 offset:31936
	v_add_f32_e32 v25, v26, v27
	v_add_f32_dpp v35, v34, v34 row_half_mirror row_mask:0xf bank_mask:0xa
	s_waitcnt lgkmcnt(6)
	v_pk_mul_f32 v[52:53], v[6:7], v[70:71]
	v_pk_mul_f32 v[56:57], v[6:7], v[74:75]
	v_pk_fma_f32 v[52:53], v[4:5], v[68:69], v[52:53]
	v_pk_mul_f32 v[54:55], v[4:5], v[72:73]
	v_add_f32_e32 v52, v52, v53
	ds_read_b128 v[60:63], v9 offset:33856
	ds_read_b128 v[64:67], v9 offset:33600
	v_add_f32_dpp v52, v52, v52 quad_perm:[1,0,3,2] row_mask:0xf bank_mask:0xf bound_ctrl:1
	v_pk_fma_f32 v[56:57], v[86:87], v[92:93], v[56:57] op_sel_hi:[1,0,1]
	v_pk_fma_f32 v[54:55], v[84:85], v[92:93], v[54:55] op_sel_hi:[1,0,1]
	v_add_f32_dpp v254, v8, v255 quad_perm:[2,3,0,1] row_mask:0xf bank_mask:0xf bound_ctrl:1
	v_add_f32_dpp v52, v52, v52 quad_perm:[2,3,0,1] row_mask:0xf bank_mask:0xf bound_ctrl:1
	ds_read_b128 v[28:31], v9 offset:34368
	ds_read_b32 v32, v10 offset:34880
	v_add_f32_dpp v52, v52, v52 row_half_mirror row_mask:0xf bank_mask:0xf bound_ctrl:1
	v_pk_mul_f32 v[26:27], v[6:7], v[42:43]
	v_add_f32_dpp v34, v25, v25 row_ror:8 row_mask:0xf bank_mask:0x3
	ds_read_b128 v[48:51], v9 offset:34112
	v_add_f32_dpp v52, v52, v52 row_mirror row_mask:0xf bank_mask:0xf bound_ctrl:1
	v_pk_fma_f32 v[6:7], v[106:107], v[52:53], v[56:57] op_sel_hi:[1,0,1]
	v_pk_fma_f32 v[26:27], v[4:5], v[40:41], v[26:27]
	v_pk_fma_f32 v[4:5], v[104:105], v[52:53], v[54:55] op_sel_hi:[1,0,1]
	ds_read_b128 v[36:39], v9 offset:33280
	v_add_f32_e32 v25, v26, v27
	v_pk_mul_f32 v[52:53], v[6:7], v[78:79]
	v_pk_mul_f32 v[56:57], v[6:7], v[82:83]
	v_pk_fma_f32 v[52:53], v[4:5], v[76:77], v[52:53]
	v_pk_mul_f32 v[54:55], v[4:5], v[80:81]
	v_add_f32_e32 v52, v52, v53
	ds_read_b128 v[68:71], v9 offset:35200
	ds_read_b128 v[72:75], v9 offset:34944
	v_add_f32_dpp v52, v52, v52 quad_perm:[1,0,3,2] row_mask:0xf bank_mask:0xf bound_ctrl:1
	v_pk_fma_f32 v[56:57], v[90:91], v[94:95], v[56:57] op_sel_hi:[1,0,1]
	v_pk_fma_f32 v[54:55], v[88:89], v[94:95], v[54:55] op_sel_hi:[1,0,1]
	v_add_f32_dpp v52, v52, v52 quad_perm:[2,3,0,1] row_mask:0xf bank_mask:0xf bound_ctrl:1
	ds_read_b128 v[84:87], v9 offset:35712
	ds_read_b32 v92, v10 offset:36224
	v_add_f32_dpp v52, v52, v52 row_half_mirror row_mask:0xf bank_mask:0xf bound_ctrl:1
	v_pk_mul_f32 v[26:27], v[6:7], v[98:99]
	v_add_f32_dpp v34, v25, v25 row_ror:8 row_mask:0xf bank_mask:0xc
	ds_read_b128 v[104:107], v9 offset:35456
	v_add_f32_dpp v52, v52, v52 row_mirror row_mask:0xf bank_mask:0xf bound_ctrl:1
	v_pk_fma_f32 v[6:7], v[110:111], v[52:53], v[56:57] op_sel_hi:[1,0,1]
	v_pk_fma_f32 v[26:27], v[4:5], v[96:97], v[26:27]
	v_pk_fma_f32 v[4:5], v[108:109], v[52:53], v[54:55] op_sel_hi:[1,0,1]
	ds_read_b128 v[40:43], v9 offset:34624
	v_add_f32_e32 v25, v26, v27
	v_add_f32_dpp v58, v34, v34 row_half_mirror row_mask:0xf bank_mask:0x5
	s_waitcnt lgkmcnt(6)
; __device__ void scan_block(const Params& P, int sb, unsigned char* lds) {
;     ...
;       for (int s = 0; s < SC_CH; ++s) {
;         f32x4 w4n, k4n, b4n, kh4n, r4n; float vn;
;         if (s + 1 < SC_CH) {
;           const float* qn = q + (s + 1) * SC_STEP;
;           w4n = *(const f32x4*)(qn); k4n = *(const f32x4*)(qn + 64); b4n = *(const f32x4*)(qn + 128); kh4n = *(const f32x4*)(qn + 192); r4n = *(const f32x4*)(qn + 256);
;           vn = qv[(s + 1) * SC_STEP];
;         }
;         __builtin_amdgcn_sched_barrier(0);
;         if (s > 0) {
;           const float y = dpp_allreduce16(ypart);
;           yk = (ks == ((s - 1) & 15)) ? y : yk;
;           if (((s - 1) & 15) == 15) yo[(size_t)(s - 16) * 1024] = yk;
;         }
;         const f32x2 pp = (f32x2){S[0], S[1]} * (f32x2){k4[0], k4[1]} + (f32x2){S[2], S[3]} * (f32x2){k4[2], k4[3]};
;         const f32x4 A = S * w4 + v * kh4;
;         const float ar = dpp_allreduce16(pp.x + pp.y);
;         S = A + ar * b4;
;         const f32x2 yy = (f32x2){S[0], S[1]} * (f32x2){r4[0], r4[1]} + (f32x2){S[2], S[3]} * (f32x2){r4[2], r4[3]};
;         ypart = yy.x + yy.y;
;         if (s + 1 < SC_CH) { w4 = w4n; k4 = k4n; b4 = b4n; kh4 = kh4n; r4 = r4n; v = vn; }
;       }
	v_pk_mul_f32 v[52:53], v[6:7], v[14:15]
	v_pk_mul_f32 v[56:57], v[6:7], v[18:19]
	v_pk_fma_f32 v[52:53], v[4:5], v[12:13], v[52:53]
	v_pk_mul_f32 v[54:55], v[4:5], v[16:17]
	v_add_f32_e32 v52, v52, v53
	ds_read_b128 v[76:79], v9 offset:36544
	ds_read_b128 v[80:83], v9 offset:36288
	v_add_f32_dpp v52, v52, v52 quad_perm:[1,0,3,2] row_mask:0xf bank_mask:0xf bound_ctrl:1
	v_pk_fma_f32 v[56:57], v[22:23], v[24:25], v[56:57] op_sel_hi:[1,0,1]
	v_pk_fma_f32 v[54:55], v[20:21], v[24:25], v[54:55] op_sel_hi:[1,0,1]
	v_cndmask_b32_e64 v255, v253, v254, s[42:43]
	v_add_f32_dpp v52, v52, v52 quad_perm:[2,3,0,1] row_mask:0xf bank_mask:0xf bound_ctrl:1
	ds_read_b128 v[88:91], v9 offset:37056
	ds_read_b32 v94, v10 offset:37568
	v_add_f32_dpp v52, v52, v52 row_half_mirror row_mask:0xf bank_mask:0xf bound_ctrl:1
	v_pk_mul_f32 v[26:27], v[6:7], v[102:103]
	v_add_f32_dpp v34, v25, v25 row_ror:8 row_mask:0xf bank_mask:0x3
	ds_read_b128 v[108:111], v9 offset:36800
	v_add_f32_dpp v52, v52, v52 row_mirror row_mask:0xf bank_mask:0xf bound_ctrl:1
	v_pk_fma_f32 v[6:7], v[46:47], v[52:53], v[56:57] op_sel_hi:[1,0,1]
	v_pk_fma_f32 v[26:27], v[4:5], v[100:101], v[26:27]
	v_pk_fma_f32 v[4:5], v[44:45], v[52:53], v[54:55] op_sel_hi:[1,0,1]
	ds_read_b128 v[96:99], v9 offset:35968
	v_add_f32_e32 v25, v26, v27
	v_pk_mul_f32 v[52:53], v[6:7], v[62:63]
	v_pk_mul_f32 v[56:57], v[6:7], v[66:67]
	v_pk_fma_f32 v[52:53], v[4:5], v[60:61], v[52:53]
	v_pk_mul_f32 v[54:55], v[4:5], v[64:65]
	v_add_f32_e32 v52, v52, v53
	ds_read_b128 v[12:15], v9 offset:37888
	ds_read_b128 v[16:19], v9 offset:37632
	v_add_f32_dpp v52, v52, v52 quad_perm:[1,0,3,2] row_mask:0xf bank_mask:0xf bound_ctrl:1
	v_pk_fma_f32 v[56:57], v[30:31], v[32:33], v[56:57] op_sel_hi:[1,0,1]
	v_pk_fma_f32 v[54:55], v[28:29], v[32:33], v[54:55] op_sel_hi:[1,0,1]
	v_add_f32_dpp v52, v52, v52 quad_perm:[2,3,0,1] row_mask:0xf bank_mask:0xf bound_ctrl:1
	ds_read_b128 v[20:23], v9 offset:38400
	ds_read_b32 v24, v10 offset:38912
	v_add_f32_dpp v52, v52, v52 row_half_mirror row_mask:0xf bank_mask:0xf bound_ctrl:1
	v_pk_mul_f32 v[26:27], v[6:7], v[38:39]
	v_add_f32_dpp v34, v25, v25 row_ror:8 row_mask:0xf bank_mask:0xc
	ds_read_b128 v[44:47], v9 offset:38144
	v_add_f32_dpp v52, v52, v52 row_mirror row_mask:0xf bank_mask:0xf bound_ctrl:1
	v_pk_fma_f32 v[6:7], v[50:51], v[52:53], v[56:57] op_sel_hi:[1,0,1]
	v_pk_fma_f32 v[26:27], v[4:5], v[36:37], v[26:27]
	v_pk_fma_f32 v[4:5], v[48:49], v[52:53], v[54:55] op_sel_hi:[1,0,1]
	ds_read_b128 v[100:103], v9 offset:37312
	v_add_f32_e32 v25, v26, v27
	v_add_f32_dpp v58, v34, v34 row_half_mirror row_mask:0xf bank_mask:0xa
	s_waitcnt lgkmcnt(6)
	v_pk_mul_f32 v[52:53], v[6:7], v[70:71]
	v_pk_mul_f32 v[56:57], v[6:7], v[74:75]
	v_pk_fma_f32 v[52:53], v[4:5], v[68:69], v[52:53]
	v_pk_mul_f32 v[54:55], v[4:5], v[72:73]
	v_add_f32_e32 v52, v52, v53
	ds_read_b128 v[60:63], v9 offset:39232
	ds_read_b128 v[64:67], v9 offset:38976
	v_add_f32_dpp v52, v52, v52 quad_perm:[1,0,3,2] row_mask:0xf bank_mask:0xf bound_ctrl:1
	v_pk_fma_f32 v[56:57], v[86:87], v[92:93], v[56:57] op_sel_hi:[1,0,1]
	v_pk_fma_f32 v[54:55], v[84:85], v[92:93], v[54:55] op_sel_hi:[1,0,1]
	v_cndmask_b32_e64 v8, v254, v253, s[42:43]
	v_add_f32_dpp v52, v52, v52 quad_perm:[2,3,0,1] row_mask:0xf bank_mask:0xf bound_ctrl:1
	ds_read_b128 v[28:31], v9 offset:39744
	ds_read_b32 v32, v10 offset:40256
	v_add_f32_dpp v52, v52, v52 row_half_mirror row_mask:0xf bank_mask:0xf bound_ctrl:1
	v_pk_mul_f32 v[26:27], v[6:7], v[42:43]
	v_add_f32_dpp v34, v25, v25 row_ror:8 row_mask:0xf bank_mask:0x3
	ds_read_b128 v[48:51], v9 offset:39488
	v_add_f32_dpp v52, v52, v52 row_mirror row_mask:0xf bank_mask:0xf bound_ctrl:1
	v_pk_fma_f32 v[6:7], v[106:107], v[52:53], v[56:57] op_sel_hi:[1,0,1]
	v_pk_fma_f32 v[26:27], v[4:5], v[40:41], v[26:27]
	v_pk_fma_f32 v[4:5], v[104:105], v[52:53], v[54:55] op_sel_hi:[1,0,1]
	ds_read_b128 v[36:39], v9 offset:38656
	v_add_f32_e32 v25, v26, v27
	v_pk_mul_f32 v[52:53], v[6:7], v[78:79]
	v_pk_mul_f32 v[56:57], v[6:7], v[82:83]
	v_pk_fma_f32 v[52:53], v[4:5], v[76:77], v[52:53]
	v_pk_mul_f32 v[54:55], v[4:5], v[80:81]
	v_add_f32_e32 v52, v52, v53
	ds_read_b128 v[68:71], v9 offset:40576
	ds_read_b128 v[72:75], v9 offset:40320
	v_add_f32_dpp v52, v52, v52 quad_perm:[1,0,3,2] row_mask:0xf bank_mask:0xf bound_ctrl:1
	v_pk_fma_f32 v[56:57], v[90:91], v[94:95], v[56:57] op_sel_hi:[1,0,1]
	v_pk_fma_f32 v[54:55], v[88:89], v[94:95], v[54:55] op_sel_hi:[1,0,1]
	v_add_f32_dpp v52, v52, v52 quad_perm:[2,3,0,1] row_mask:0xf bank_mask:0xf bound_ctrl:1
	ds_read_b128 v[84:87], v9 offset:41088
	ds_read_b32 v92, v10 offset:41600
	v_add_f32_dpp v52, v52, v52 row_half_mirror row_mask:0xf bank_mask:0xf bound_ctrl:1
	v_pk_mul_f32 v[26:27], v[6:7], v[98:99]
	v_add_f32_dpp v34, v25, v25 row_ror:8 row_mask:0xf bank_mask:0xc
	ds_read_b128 v[104:107], v9 offset:40832
	v_add_f32_dpp v52, v52, v52 row_mirror row_mask:0xf bank_mask:0xf bound_ctrl:1
	v_pk_fma_f32 v[6:7], v[110:111], v[52:53], v[56:57] op_sel_hi:[1,0,1]
	v_pk_fma_f32 v[26:27], v[4:5], v[96:97], v[26:27]
	v_pk_fma_f32 v[4:5], v[108:109], v[52:53], v[54:55] op_sel_hi:[1,0,1]
	ds_read_b128 v[40:43], v9 offset:40000
	v_add_f32_e32 v25, v26, v27
	v_add_f32_dpp v0, v34, v34 row_half_mirror row_mask:0xf bank_mask:0x5
	s_waitcnt lgkmcnt(8)
; __device__ void scan_block(const Params& P, int sb, unsigned char* lds) {
;     ...
;       for (int s = 0; s < SC_CH; ++s) {
;         f32x4 w4n, k4n, b4n, kh4n, r4n; float vn;
;         if (s + 1 < SC_CH) {
;           const float* qn = q + (s + 1) * SC_STEP;
;           w4n = *(const f32x4*)(qn); k4n = *(const f32x4*)(qn + 64); b4n = *(const f32x4*)(qn + 128); kh4n = *(const f32x4*)(qn + 192); r4n = *(const f32x4*)(qn + 256);
;           vn = qv[(s + 1) * SC_STEP];
;         }
;         __builtin_amdgcn_sched_barrier(0);
;         if (s > 0) {
;           const float y = dpp_allreduce16(ypart);
;           yk = (ks == ((s - 1) & 15)) ? y : yk;
;           if (((s - 1) & 15) == 15) yo[(size_t)(s - 16) * 1024] = yk;
;         }
;         const f32x2 pp = (f32x2){S[0], S[1]} * (f32x2){k4[0], k4[1]} + (f32x2){S[2], S[3]} * (f32x2){k4[2], k4[3]};
;         const f32x4 A = S * w4 + v * kh4;
;         const float ar = dpp_allreduce16(pp.x + pp.y);
;         S = A + ar * b4;
;         const f32x2 yy = (f32x2){S[0], S[1]} * (f32x2){r4[0], r4[1]} + (f32x2){S[2], S[3]} * (f32x2){r4[2], r4[3]};
;         ypart = yy.x + yy.y;
;         if (s + 1 < SC_CH) { w4 = w4n; k4 = k4n; b4 = b4n; kh4 = kh4n; r4 = r4n; v = vn; }
;       }
;       { const float y = dpp_allreduce16(ypart); yk = (ks == 15) ? y : yk; yo[(size_t)16 * 1024] = yk; }
;       __syncthreads();
	v_pk_mul_f32 v[52:53], v[6:7], v[14:15]
	v_pk_mul_f32 v[56:57], v[6:7], v[18:19]
	v_pk_fma_f32 v[52:53], v[4:5], v[12:13], v[52:53]
	v_pk_mul_f32 v[54:55], v[4:5], v[16:17]
	v_add_f32_e32 v52, v52, v53
	ds_read_b128 v[76:79], v9 offset:41920
	ds_read_b128 v[80:83], v9 offset:41664
	v_add_f32_dpp v52, v52, v52 quad_perm:[1,0,3,2] row_mask:0xf bank_mask:0xf bound_ctrl:1
	v_pk_fma_f32 v[56:57], v[22:23], v[24:25], v[56:57] op_sel_hi:[1,0,1]
	v_pk_fma_f32 v[54:55], v[20:21], v[24:25], v[54:55] op_sel_hi:[1,0,1]
	v_add_f32_dpp v33, v8, v255 quad_perm:[1,0,3,2] row_mask:0xf bank_mask:0xf bound_ctrl:1
	v_add_f32_dpp v52, v52, v52 quad_perm:[2,3,0,1] row_mask:0xf bank_mask:0xf bound_ctrl:1
	ds_read_b128 v[88:91], v9 offset:42432
	ds_read_b32 v94, v10 offset:42944
	v_add_f32_dpp v52, v52, v52 row_half_mirror row_mask:0xf bank_mask:0xf bound_ctrl:1
	v_pk_mul_f32 v[26:27], v[6:7], v[102:103]
	v_add_f32_dpp v34, v25, v25 row_ror:8 row_mask:0xf bank_mask:0x3
	ds_read_b128 v[108:111], v9 offset:42176
	v_add_f32_dpp v52, v52, v52 row_mirror row_mask:0xf bank_mask:0xf bound_ctrl:1
	v_pk_fma_f32 v[6:7], v[46:47], v[52:53], v[56:57] op_sel_hi:[1,0,1]
	v_pk_fma_f32 v[26:27], v[4:5], v[100:101], v[26:27]
	v_pk_fma_f32 v[4:5], v[44:45], v[52:53], v[54:55] op_sel_hi:[1,0,1]
	ds_read_b128 v[96:99], v9 offset:41344
	ds_read_b128 v[100:103], v9 offset:42688
	v_add_f32_e32 v25, v26, v27
	v_pk_mul_f32 v[52:53], v[6:7], v[62:63]
	v_pk_mul_f32 v[56:57], v[6:7], v[66:67]
	v_pk_fma_f32 v[52:53], v[4:5], v[60:61], v[52:53]
	v_pk_mul_f32 v[54:55], v[4:5], v[64:65]
	v_add_f32_e32 v52, v52, v53
	s_nop 1
	v_add_f32_dpp v52, v52, v52 quad_perm:[1,0,3,2] row_mask:0xf bank_mask:0xf bound_ctrl:1
	v_pk_fma_f32 v[56:57], v[30:31], v[32:33], v[56:57] op_sel_hi:[1,0,1]
	v_pk_fma_f32 v[54:55], v[28:29], v[32:33], v[54:55] op_sel_hi:[1,0,1]
	v_add_f32_dpp v52, v52, v52 quad_perm:[2,3,0,1] row_mask:0xf bank_mask:0xf bound_ctrl:1
	s_waitcnt lgkmcnt(0)
	s_barrier
	v_xor_b32_e32 v9, 0xa800, v9
	v_xor_b32_e32 v10, 0xa800, v10
	ds_read_b128 v[12:15], v9 offset:256
	ds_read_b128 v[16:19], v9 offset:0
	ds_read_b128 v[20:23], v9 offset:768
	ds_read_b32 v24, v10 offset:1280
	v_add_f32_dpp v52, v52, v52 row_half_mirror row_mask:0xf bank_mask:0xf bound_ctrl:1
	v_pk_mul_f32 v[26:27], v[6:7], v[38:39]
	v_add_f32_dpp v34, v25, v25 row_ror:8 row_mask:0xf bank_mask:0xc
	ds_read_b128 v[44:47], v9 offset:512
	v_add_f32_dpp v52, v52, v52 row_mirror row_mask:0xf bank_mask:0xf bound_ctrl:1
	v_pk_fma_f32 v[6:7], v[50:51], v[52:53], v[56:57] op_sel_hi:[1,0,1]
	v_pk_fma_f32 v[26:27], v[4:5], v[36:37], v[26:27]
	v_pk_fma_f32 v[4:5], v[48:49], v[52:53], v[54:55] op_sel_hi:[1,0,1]
	v_add_f32_e32 v25, v26, v27
	v_add_f32_dpp v0, v34, v34 row_half_mirror row_mask:0xf bank_mask:0xa
	s_waitcnt lgkmcnt(5)
	v_pk_mul_f32 v[52:53], v[6:7], v[70:71]
	v_pk_mul_f32 v[56:57], v[6:7], v[74:75]
	v_pk_fma_f32 v[52:53], v[4:5], v[68:69], v[52:53]
	v_pk_mul_f32 v[54:55], v[4:5], v[72:73]
	v_add_f32_e32 v52, v52, v53
	ds_read_b128 v[60:63], v9 offset:1600
	ds_read_b128 v[64:67], v9 offset:1344
	v_add_f32_dpp v52, v52, v52 quad_perm:[1,0,3,2] row_mask:0xf bank_mask:0xf bound_ctrl:1
	v_pk_fma_f32 v[56:57], v[86:87], v[92:93], v[56:57] op_sel_hi:[1,0,1]
	v_pk_fma_f32 v[54:55], v[84:85], v[92:93], v[54:55] op_sel_hi:[1,0,1]
	global_store_dword v2, v33, s[4:5]
	v_add_f32_dpp v52, v52, v52 quad_perm:[2,3,0,1] row_mask:0xf bank_mask:0xf bound_ctrl:1
	ds_read_b128 v[28:31], v9 offset:2112
	ds_read_b32 v32, v10 offset:2624
	v_add_f32_dpp v52, v52, v52 row_half_mirror row_mask:0xf bank_mask:0xf bound_ctrl:1
	v_pk_mul_f32 v[26:27], v[6:7], v[42:43]
	v_add_f32_dpp v34, v25, v25 row_ror:8 row_mask:0xf bank_mask:0x3
	ds_read_b128 v[48:51], v9 offset:1856
	v_add_f32_dpp v52, v52, v52 row_mirror row_mask:0xf bank_mask:0xf bound_ctrl:1
	v_pk_fma_f32 v[6:7], v[106:107], v[52:53], v[56:57] op_sel_hi:[1,0,1]
	v_pk_fma_f32 v[26:27], v[4:5], v[40:41], v[26:27]
	v_pk_fma_f32 v[4:5], v[104:105], v[52:53], v[54:55] op_sel_hi:[1,0,1]
	ds_read_b128 v[36:39], v9 offset:1024
	v_add_f32_e32 v25, v26, v27
	v_pk_mul_f32 v[52:53], v[6:7], v[78:79]
	v_pk_mul_f32 v[56:57], v[6:7], v[82:83]
	v_pk_fma_f32 v[52:53], v[4:5], v[76:77], v[52:53]
	v_pk_mul_f32 v[54:55], v[4:5], v[80:81]
	v_add_f32_e32 v52, v52, v53
	ds_read_b128 v[68:71], v9 offset:2944
	ds_read_b128 v[72:75], v9 offset:2688
	v_add_f32_dpp v52, v52, v52 quad_perm:[1,0,3,2] row_mask:0xf bank_mask:0xf bound_ctrl:1
	v_pk_fma_f32 v[56:57], v[90:91], v[94:95], v[56:57] op_sel_hi:[1,0,1]
	v_pk_fma_f32 v[54:55], v[88:89], v[94:95], v[54:55] op_sel_hi:[1,0,1]
	v_add_f32_dpp v52, v52, v52 quad_perm:[2,3,0,1] row_mask:0xf bank_mask:0xf bound_ctrl:1
	ds_read_b128 v[84:87], v9 offset:3456
	ds_read_b32 v92, v10 offset:3968
	v_add_f32_dpp v52, v52, v52 row_half_mirror row_mask:0xf bank_mask:0xf bound_ctrl:1
	v_pk_mul_f32 v[26:27], v[6:7], v[98:99]
	v_add_f32_dpp v34, v25, v25 row_ror:8 row_mask:0xf bank_mask:0xc
	ds_read_b128 v[104:107], v9 offset:3200
	v_add_f32_dpp v52, v52, v52 row_mirror row_mask:0xf bank_mask:0xf bound_ctrl:1
	v_pk_fma_f32 v[6:7], v[110:111], v[52:53], v[56:57] op_sel_hi:[1,0,1]
	v_pk_fma_f32 v[26:27], v[4:5], v[96:97], v[26:27]
	v_pk_fma_f32 v[4:5], v[108:109], v[52:53], v[54:55] op_sel_hi:[1,0,1]
	ds_read_b128 v[40:43], v9 offset:2368
	v_add_f32_e32 v25, v26, v27
	v_add_f32_dpp v11, v34, v34 row_half_mirror row_mask:0xf bank_mask:0x5
	s_nop 0
	v_add_f32_dpp v34, v25, v25 row_ror:8 row_mask:0xf bank_mask:0x3
	v_pk_mul_f32 v[26:27], v[6:7], v[102:103]
	v_cndmask_b32_e64 v255, v35, v58, s[40:41]
	v_cndmask_b32_e64 v8, v58, v35, s[40:41]
	v_pk_fma_f32 v[26:27], v[4:5], v[100:101], v[26:27]
	s_nop 0
	v_add_f32_e32 v25, v26, v27
	v_add_f32_dpp v253, v8, v255 quad_perm:[2,3,0,1] row_mask:0xf bank_mask:0xf bound_ctrl:1
	s_nop 0
	v_add_f32_dpp v34, v25, v25 row_ror:8 row_mask:0xf bank_mask:0xc
	s_nop 1
	v_add_f32_dpp v11, v34, v34 row_half_mirror row_mask:0xf bank_mask:0xa
	s_nop 1
	v_cndmask_b32_e64 v255, v0, v11, s[40:41]
	v_cndmask_b32_e64 v8, v11, v0, s[40:41]
	s_nop 1
	v_add_f32_dpp v254, v8, v255 quad_perm:[2,3,0,1] row_mask:0xf bank_mask:0xf bound_ctrl:1
	v_cndmask_b32_e64 v255, v253, v254, s[42:43]
	v_cndmask_b32_e64 v8, v254, v253, s[42:43]
	s_add_i32 s3, s3, 1
	s_nop 0
	v_add_f32_dpp v33, v8, v255 quad_perm:[1,0,3,2] row_mask:0xf bank_mask:0xf bound_ctrl:1
	global_store_dword v3, v33, s[4:5]
	s_add_u32 s4, s4, 0x20000
	s_addc_u32 s5, s5, 0
	s_cmp_lg_u32 s3, 0x100
	s_cbranch_scc1 .Lscan_top
	s_waitcnt lgkmcnt(0)
	s_setprio 0
	v_readlane_b32 s60, v250, 1
	v_readlane_b32 s61, v250, 2
	s_mov_b64 s[62:63], s[90:91]
